# up conv epilogue: wave-uniform sequence-edge test per unit; per-row-block per-lane edge detection only for windows touching an edge
# speedup vs baseline: 1.0022x; 1.0022x over previous
.LBB0_163:
	v_mov_b32_e32 v0, v191
	s_barrier
	s_mul_i32 s100, s30, 0xfe
	v_readfirstlane_b32 s101, v191
	s_lshr_b32 s101, s101, 6
	s_lshl_b32 s101, s101, 5
	s_add_i32 s100, s100, s101
	s_add_i32 s101, s100, 32
	s_add_i32 s6, s100, -1
	s_cmp_lt_i32 s100, 0x4000
	s_cselect_b32 s7, 12, 8
	s_ashr_i32 s6, s6, s7
	s_ashr_i32 s101, s101, s7
	s_sub_i32 s100, s101, s6
	v_and_b32_e32 v224, 15, v191
	s_lshl_b32 s9, s8, 7
	v_lshl_or_b32 v225, v224, 3, s9
	v_lshlrev_b32_e32 v226, 2, v225
	global_load_dwordx4 v[134:137], v226, s[12:13]
	global_load_dwordx4 v[138:141], v226, s[12:13] offset:16
	global_load_dwordx4 v[142:145], v226, s[16:17]
	global_load_dwordx4 v[146:149], v226, s[16:17] offset:16
	global_load_dwordx4 v[150:153], v226, s[18:19]
	global_load_dwordx4 v[154:157], v226, s[18:19] offset:16
	global_load_dwordx4 v[158:161], v226, s[20:21]
	global_load_dwordx4 v[162:165], v226, s[20:21] offset:16
	global_load_dwordx4 v[192:195], v226, s[22:23]
	global_load_dwordx4 v[196:199], v226, s[22:23] offset:16
	global_load_dwordx4 v[200:203], v226, s[24:25]
	global_load_dwordx4 v[204:207], v226, s[24:25] offset:16
	global_load_dwordx4 v[208:211], v226, s[14:15]
	global_load_dwordx4 v[212:215], v226, s[14:15] offset:16
	global_load_dwordx4 v[216:219], v226, s[26:27]
	global_load_dwordx4 v[220:223], v226, s[26:27] offset:16
	s_lshl_b32 s6, s67, 6
	v_and_b32_e32 v130, 15, v0
	v_or_b32_e32 v132, s70, v130
	s_movk_i32 s7, 0x220
	v_and_b32_e32 v131, 48, v0
	s_add_i32 s6, s6, 0
	v_mul_lo_u32 v132, v132, s7
	v_add3_u32 v131, s6, v131, v132
	v_cvt_pk_bf16_f32 v62, v62, v63
	v_cvt_pk_bf16_f32 v63, v64, v65
	v_cvt_pk_bf16_f32 v64, v58, v59
	v_add_u32_e32 v58, 0x11100, v131
	v_cvt_pk_bf16_f32 v46, v46, v47
	v_cvt_pk_bf16_f32 v47, v48, v49
	v_cvt_pk_bf16_f32 v48, v42, v43
	v_cvt_pk_bf16_f32 v49, v44, v45
	ds_write_b128 v58, v[46:49]
	v_add_u32_e32 v46, 0x13200, v131
	v_cvt_pk_bf16_f32 v42, v54, v55
	v_cvt_pk_bf16_f32 v43, v56, v57
	v_cvt_pk_bf16_f32 v44, v50, v51
	v_cvt_pk_bf16_f32 v45, v52, v53
	ds_write_b128 v46, v[42:45]
	v_add_u32_e32 v42, 0x13300, v131
	v_cvt_pk_bf16_f32 v30, v30, v31
	v_cvt_pk_bf16_f32 v31, v32, v33
	v_cvt_pk_bf16_f32 v32, v26, v27
	v_cvt_pk_bf16_f32 v33, v28, v29
	v_cvt_pk_bf16_f32 v94, v94, v95
	v_cvt_pk_bf16_f32 v95, v96, v97
	v_cvt_pk_bf16_f32 v96, v90, v91
	v_cvt_pk_bf16_f32 v97, v92, v93
	ds_write_b128 v42, v[30:33]
	v_add_u32_e32 v30, 0x15400, v131
	v_cvt_pk_bf16_f32 v26, v38, v39
	v_cvt_pk_bf16_f32 v27, v40, v41
	v_cvt_pk_bf16_f32 v28, v34, v35
	v_cvt_pk_bf16_f32 v29, v36, v37
	s_lshl_b32 s6, s8, 7
	ds_write_b128 v131, v[94:97] offset:8960
	ds_write_b128 v30, v[26:29]
	v_add_u32_e32 v26, 0x15500, v131
	v_cvt_pk_bf16_f32 v14, v14, v15
	v_cvt_pk_bf16_f32 v15, v16, v17
	v_cvt_pk_bf16_f32 v16, v10, v11
	v_cvt_pk_bf16_f32 v17, v12, v13
	v_lshl_or_b32 v94, v130, 3, s6
	ds_write_b128 v26, v[14:17]
	v_add_u32_e32 v14, 0x17600, v131
	v_cvt_pk_bf16_f32 v10, v22, v23
	v_cvt_pk_bf16_f32 v11, v24, v25
	v_cvt_pk_bf16_f32 v12, v18, v19
	v_cvt_pk_bf16_f32 v13, v20, v21
	v_ashrrev_i32_e32 v95, 31, v94
	v_cvt_pk_bf16_f32 v126, v126, v127
	v_cvt_pk_bf16_f32 v127, v128, v129
	v_cvt_pk_bf16_f32 v128, v122, v123
	v_cvt_pk_bf16_f32 v129, v124, v125
	v_cvt_pk_bf16_f32 v110, v110, v111
	v_cvt_pk_bf16_f32 v111, v112, v113
	v_cvt_pk_bf16_f32 v112, v106, v107
	v_cvt_pk_bf16_f32 v113, v108, v109
	v_cvt_pk_bf16_f32 v106, v118, v119
	v_cvt_pk_bf16_f32 v107, v120, v121
	v_cvt_pk_bf16_f32 v108, v114, v115
	v_cvt_pk_bf16_f32 v109, v116, v117
	v_cvt_pk_bf16_f32 v90, v102, v103
	v_cvt_pk_bf16_f32 v91, v104, v105
	v_cvt_pk_bf16_f32 v92, v98, v99
	v_cvt_pk_bf16_f32 v93, v100, v101
	v_cvt_pk_bf16_f32 v78, v78, v79
	v_cvt_pk_bf16_f32 v79, v80, v81
	v_cvt_pk_bf16_f32 v80, v74, v75
	v_cvt_pk_bf16_f32 v81, v76, v77
	v_cvt_pk_bf16_f32 v74, v86, v87
	v_cvt_pk_bf16_f32 v75, v88, v89
	v_cvt_pk_bf16_f32 v76, v82, v83
	v_cvt_pk_bf16_f32 v77, v84, v85
	v_cvt_pk_bf16_f32 v70, v70, v71
	v_cvt_pk_bf16_f32 v71, v72, v73
	v_cvt_pk_bf16_f32 v72, v66, v67
	v_cvt_pk_bf16_f32 v73, v68, v69
	v_add_u32_e32 v66, 0x11000, v131
	v_cvt_pk_bf16_f32 v65, v60, v61
	ds_write_b128 v14, v[10:13]
	v_add_u32_e32 v10, 0x17700, v131
	v_cvt_pk_bf16_f32 v6, v6, v7
	v_cvt_pk_bf16_f32 v7, v8, v9
	v_cvt_pk_bf16_f32 v8, v2, v3
	v_cvt_pk_bf16_f32 v9, v4, v5
	v_lshlrev_b64 v[22:23], 2, v[94:95]
	ds_write_b128 v131, v[126:129]
	ds_write_b128 v131, v[110:113] offset:256
	ds_write_b128 v131, v[106:109] offset:8704
	ds_write_b128 v131, v[90:93] offset:17408
	ds_write_b128 v131, v[78:81] offset:17664
	ds_write_b128 v131, v[74:77] offset:26112
	ds_write_b128 v131, v[70:73] offset:26368
	ds_write_b128 v66, v[62:65]
	ds_write_b128 v10, v[6:9]
	v_lshl_add_u64 v[2:3], s[12:13], 0, v[22:23]
	v_lshl_add_u64 v[6:7], s[16:17], 0, v[22:23]
	s_waitcnt lgkmcnt(0)
	s_waitcnt vmcnt(0) lgkmcnt(0)
	s_barrier
	v_and_b32_e32 v47, 15, v191
	v_lshrrev_b32_e32 v48, 4, v191
	s_lshl_b32 s6, s8, 7
	v_lshl_or_b32 v44, v47, 3, s6
	v_lshlrev_b32_e32 v49, 3, v48
	s_movk_i32 s44, 0x220
	s_movk_i32 s49, 0x4000
	v_mul_lo_u32 v54, v49, s44
	v_lshl_add_u32 v54, v47, 4, v54
	v_add_u32_e32 v49, 1, v49
	s_mul_i32 s9, s30, 0xfe
	s_add_i32 s9, s9, -1
	v_add_u32_e32 v45, s9, v49
	v_readlane_b32 s28, v255, 19
	s_movk_i32 s38, 0x1600
	v_mov_b64_e32 v[50:51], s[10:11]
	v_mad_i64_i32 v[50:51], s[6:7], v45, s38, v[50:51]
	v_lshlrev_b32_e32 v52, 1, v44
	v_mov_b32_e32 v53, 0
	v_lshl_add_u64 v[50:51], v[50:51], 0, v[52:53]
	s_mov_b32 s39, 0
	v_mov_b32_e32 v42, 0xbfb8aa3b
	ds_read_b128 v[114:117], v54 offset:0
	ds_read_b128 v[118:121], v54 offset:256
	ds_read_b128 v[122:125], v54 offset:544
	ds_read_b128 v[126:129], v54 offset:800
	s_waitcnt lgkmcnt(2)
	v_lshlrev_b32_e32 v66, 16, v114
	v_and_b32_e32 v67, 0xffff0000, v114
	v_lshlrev_b32_e32 v68, 16, v115
	v_and_b32_e32 v69, 0xffff0000, v115
	v_lshlrev_b32_e32 v70, 16, v116
	v_and_b32_e32 v71, 0xffff0000, v116
	v_lshlrev_b32_e32 v72, 16, v117
	v_and_b32_e32 v73, 0xffff0000, v117
	v_lshlrev_b32_e32 v74, 16, v118
	v_and_b32_e32 v75, 0xffff0000, v118
	v_lshlrev_b32_e32 v76, 16, v119
	v_and_b32_e32 v77, 0xffff0000, v119
	v_lshlrev_b32_e32 v78, 16, v120
	v_and_b32_e32 v79, 0xffff0000, v120
	v_lshlrev_b32_e32 v80, 16, v121
	v_and_b32_e32 v81, 0xffff0000, v121
	ds_read_b128 v[114:117], v54 offset:1088
	ds_read_b128 v[118:121], v54 offset:1344
	s_waitcnt lgkmcnt(2)
	v_lshlrev_b32_e32 v82, 16, v122
	v_and_b32_e32 v83, 0xffff0000, v122
	v_lshlrev_b32_e32 v84, 16, v123
	v_and_b32_e32 v85, 0xffff0000, v123
	v_lshlrev_b32_e32 v86, 16, v124
	v_and_b32_e32 v87, 0xffff0000, v124
	v_lshlrev_b32_e32 v88, 16, v125
	v_and_b32_e32 v89, 0xffff0000, v125
	v_lshlrev_b32_e32 v90, 16, v126
	v_and_b32_e32 v91, 0xffff0000, v126
	v_lshlrev_b32_e32 v92, 16, v127
	v_and_b32_e32 v93, 0xffff0000, v127
	v_lshlrev_b32_e32 v94, 16, v128
	v_and_b32_e32 v95, 0xffff0000, v128
	v_lshlrev_b32_e32 v96, 16, v129
	v_and_b32_e32 v97, 0xffff0000, v129
	s_waitcnt vmcnt(0)
	s_waitcnt lgkmcnt(0)
	v_lshlrev_b32_e32 v98, 16, v114
	v_and_b32_e32 v99, 0xffff0000, v114
	v_lshlrev_b32_e32 v100, 16, v115
	v_and_b32_e32 v101, 0xffff0000, v115
	v_lshlrev_b32_e32 v102, 16, v116
	v_and_b32_e32 v103, 0xffff0000, v116
	v_lshlrev_b32_e32 v104, 16, v117
	v_and_b32_e32 v105, 0xffff0000, v117
	v_lshlrev_b32_e32 v106, 16, v118
	v_and_b32_e32 v107, 0xffff0000, v118
	v_lshlrev_b32_e32 v108, 16, v119
	v_and_b32_e32 v109, 0xffff0000, v119
	v_lshlrev_b32_e32 v110, 16, v120
	v_and_b32_e32 v111, 0xffff0000, v120
	v_lshlrev_b32_e32 v112, 16, v121
	v_and_b32_e32 v113, 0xffff0000, v121
	ds_read_b128 v[122:125], v54 offset:1632
	ds_read_b128 v[126:129], v54 offset:1888
	s_movk_i32 s6, 255
	v_cmp_gt_i32_e32 vcc, s6, v49
	s_mov_b32 s6, s28
	v_cmp_gt_i32_e64 s[6:7], s6, v45
	s_and_b64 s[6:7], vcc, s[6:7]
	s_and_saveexec_b64 s[28:29], s[6:7]
	s_cbranch_execz .Luc_skip0
	s_mov_b64 s[78:79], 0
	s_cmp_eq_u32 s100, 0
	s_cbranch_scc1 .Luc_fast0
	v_add_u32_e32 v52, 0, v45
	v_mov_b32_e32 v53, 0xff
	v_cmp_gt_i32_e32 vcc, s49, v52
	v_mov_b32_e32 v46, 0xfff
	s_nop 0
	v_cndmask_b32_e32 v53, v53, v46, vcc
	v_and_b32_e32 v52, v52, v53
	v_cmp_ne_u32_e32 vcc, 0, v52
	v_cmp_ne_u32_e64 s[6:7], v52, v53
	s_mov_b64 s[78:79], 0
	s_and_b64 s[76:77], vcc, s[6:7]
	s_xor_b64 s[76:77], s[76:77], exec
	s_cbranch_scc0 .Luc_fast0
	v_cndmask_b32_e32 v66, 0, v66, vcc
	v_cndmask_b32_e32 v67, 0, v67, vcc
	v_cndmask_b32_e32 v68, 0, v68, vcc
	v_cndmask_b32_e32 v69, 0, v69, vcc
	v_cndmask_b32_e32 v70, 0, v70, vcc
	v_cndmask_b32_e32 v71, 0, v71, vcc
	v_cndmask_b32_e32 v72, 0, v72, vcc
	v_cndmask_b32_e32 v73, 0, v73, vcc
	v_cndmask_b32_e32 v74, 0, v74, vcc
	v_cndmask_b32_e32 v75, 0, v75, vcc
	v_cndmask_b32_e32 v76, 0, v76, vcc
	v_cndmask_b32_e32 v77, 0, v77, vcc
	v_cndmask_b32_e32 v78, 0, v78, vcc
	v_cndmask_b32_e32 v79, 0, v79, vcc
	v_cndmask_b32_e32 v80, 0, v80, vcc
	v_cndmask_b32_e32 v81, 0, v81, vcc
	v_mov_b64_e32 v[2:3], v[98:99]
	v_mov_b64_e32 v[4:5], v[100:101]
	v_mov_b64_e32 v[6:7], v[102:103]
	v_mov_b64_e32 v[8:9], v[104:105]
	v_mov_b64_e32 v[10:11], v[106:107]
	v_mov_b64_e32 v[12:13], v[108:109]
	v_mov_b64_e32 v[14:15], v[110:111]
	v_mov_b64_e32 v[16:17], v[112:113]
	v_cndmask_b32_e64 v98, 0, v98, s[6:7]
	v_cndmask_b32_e64 v99, 0, v99, s[6:7]
	v_cndmask_b32_e64 v100, 0, v100, s[6:7]
	v_cndmask_b32_e64 v101, 0, v101, s[6:7]
	v_cndmask_b32_e64 v102, 0, v102, s[6:7]
	v_cndmask_b32_e64 v103, 0, v103, s[6:7]
	v_cndmask_b32_e64 v104, 0, v104, s[6:7]
	v_cndmask_b32_e64 v105, 0, v105, s[6:7]
	v_cndmask_b32_e64 v106, 0, v106, s[6:7]
	v_cndmask_b32_e64 v107, 0, v107, s[6:7]
	v_cndmask_b32_e64 v108, 0, v108, s[6:7]
	v_cndmask_b32_e64 v109, 0, v109, s[6:7]
	v_cndmask_b32_e64 v110, 0, v110, s[6:7]
	v_cndmask_b32_e64 v111, 0, v111, s[6:7]
	v_cndmask_b32_e64 v112, 0, v112, s[6:7]
	v_cndmask_b32_e64 v113, 0, v113, s[6:7]
	s_mov_b64 s[78:79], -1

.Luc_skip0:
	s_or_b64 exec, exec, s[28:29]
	v_readlane_b32 s28, v255, 19
	v_lshl_add_u64 v[50:51], v[50:51], 0, s[38:39]
	s_waitcnt lgkmcnt(0)
	v_lshlrev_b32_e32 v66, 16, v122
	v_and_b32_e32 v67, 0xffff0000, v122
	v_lshlrev_b32_e32 v68, 16, v123
	v_and_b32_e32 v69, 0xffff0000, v123
	v_lshlrev_b32_e32 v70, 16, v124
	v_and_b32_e32 v71, 0xffff0000, v124
	v_lshlrev_b32_e32 v72, 16, v125
	v_and_b32_e32 v73, 0xffff0000, v125
	v_lshlrev_b32_e32 v74, 16, v126
	v_and_b32_e32 v75, 0xffff0000, v126
	v_lshlrev_b32_e32 v76, 16, v127
	v_and_b32_e32 v77, 0xffff0000, v127
	v_lshlrev_b32_e32 v78, 16, v128
	v_and_b32_e32 v79, 0xffff0000, v128
	v_lshlrev_b32_e32 v80, 16, v129
	v_and_b32_e32 v81, 0xffff0000, v129
	ds_read_b128 v[114:117], v54 offset:2176
	ds_read_b128 v[118:121], v54 offset:2432
	s_movk_i32 s6, 254
	v_cmp_gt_i32_e32 vcc, s6, v49
	s_sub_i32 s6, s28, 1
	v_cmp_gt_i32_e64 s[6:7], s6, v45
	s_and_b64 s[6:7], vcc, s[6:7]
	s_and_saveexec_b64 s[28:29], s[6:7]
	s_cbranch_execz .Luc_skip1
	s_mov_b64 s[78:79], 0
	s_cmp_eq_u32 s100, 0
	s_cbranch_scc1 .Luc_fast1
	v_add_u32_e32 v52, 1, v45
	v_mov_b32_e32 v53, 0xff
	v_cmp_gt_i32_e32 vcc, s49, v52
	v_mov_b32_e32 v46, 0xfff
	s_nop 0
	v_cndmask_b32_e32 v53, v53, v46, vcc
	v_and_b32_e32 v52, v52, v53
	v_cmp_ne_u32_e32 vcc, 0, v52
	v_cmp_ne_u32_e64 s[6:7], v52, v53
	s_mov_b64 s[78:79], 0
	s_and_b64 s[76:77], vcc, s[6:7]
	s_xor_b64 s[76:77], s[76:77], exec
	s_cbranch_scc0 .Luc_fast1
	v_cndmask_b32_e32 v82, 0, v82, vcc
	v_cndmask_b32_e32 v83, 0, v83, vcc
	v_cndmask_b32_e32 v84, 0, v84, vcc
	v_cndmask_b32_e32 v85, 0, v85, vcc
	v_cndmask_b32_e32 v86, 0, v86, vcc
	v_cndmask_b32_e32 v87, 0, v87, vcc
	v_cndmask_b32_e32 v88, 0, v88, vcc
	v_cndmask_b32_e32 v89, 0, v89, vcc
	v_cndmask_b32_e32 v90, 0, v90, vcc
	v_cndmask_b32_e32 v91, 0, v91, vcc
	v_cndmask_b32_e32 v92, 0, v92, vcc
	v_cndmask_b32_e32 v93, 0, v93, vcc
	v_cndmask_b32_e32 v94, 0, v94, vcc
	v_cndmask_b32_e32 v95, 0, v95, vcc
	v_cndmask_b32_e32 v96, 0, v96, vcc
	v_cndmask_b32_e32 v97, 0, v97, vcc
	v_mov_b64_e32 v[2:3], v[66:67]
	v_mov_b64_e32 v[4:5], v[68:69]
	v_mov_b64_e32 v[6:7], v[70:71]
	v_mov_b64_e32 v[8:9], v[72:73]
	v_mov_b64_e32 v[10:11], v[74:75]
	v_mov_b64_e32 v[12:13], v[76:77]
	v_mov_b64_e32 v[14:15], v[78:79]
	v_mov_b64_e32 v[16:17], v[80:81]
	v_cndmask_b32_e64 v66, 0, v66, s[6:7]
	v_cndmask_b32_e64 v67, 0, v67, s[6:7]
	v_cndmask_b32_e64 v68, 0, v68, s[6:7]
	v_cndmask_b32_e64 v69, 0, v69, s[6:7]
	v_cndmask_b32_e64 v70, 0, v70, s[6:7]
	v_cndmask_b32_e64 v71, 0, v71, s[6:7]
	v_cndmask_b32_e64 v72, 0, v72, s[6:7]
	v_cndmask_b32_e64 v73, 0, v73, s[6:7]
	v_cndmask_b32_e64 v74, 0, v74, s[6:7]
	v_cndmask_b32_e64 v75, 0, v75, s[6:7]
	v_cndmask_b32_e64 v76, 0, v76, s[6:7]
	v_cndmask_b32_e64 v77, 0, v77, s[6:7]
	v_cndmask_b32_e64 v78, 0, v78, s[6:7]
	v_cndmask_b32_e64 v79, 0, v79, s[6:7]
	v_cndmask_b32_e64 v80, 0, v80, s[6:7]
	v_cndmask_b32_e64 v81, 0, v81, s[6:7]
	s_mov_b64 s[78:79], -1

.Luc_skip1:
	s_or_b64 exec, exec, s[28:29]
	v_readlane_b32 s28, v255, 19
	v_lshl_add_u64 v[50:51], v[50:51], 0, s[38:39]
	s_waitcnt lgkmcnt(0)
	v_lshlrev_b32_e32 v82, 16, v114
	v_and_b32_e32 v83, 0xffff0000, v114
	v_lshlrev_b32_e32 v84, 16, v115
	v_and_b32_e32 v85, 0xffff0000, v115
	v_lshlrev_b32_e32 v86, 16, v116
	v_and_b32_e32 v87, 0xffff0000, v116
	v_lshlrev_b32_e32 v88, 16, v117
	v_and_b32_e32 v89, 0xffff0000, v117
	v_lshlrev_b32_e32 v90, 16, v118
	v_and_b32_e32 v91, 0xffff0000, v118
	v_lshlrev_b32_e32 v92, 16, v119
	v_and_b32_e32 v93, 0xffff0000, v119
	v_lshlrev_b32_e32 v94, 16, v120
	v_and_b32_e32 v95, 0xffff0000, v120
	v_lshlrev_b32_e32 v96, 16, v121
	v_and_b32_e32 v97, 0xffff0000, v121
	ds_read_b128 v[122:125], v54 offset:2720
	ds_read_b128 v[126:129], v54 offset:2976
	s_movk_i32 s6, 253
	v_cmp_gt_i32_e32 vcc, s6, v49
	s_sub_i32 s6, s28, 2
	v_cmp_gt_i32_e64 s[6:7], s6, v45
	s_and_b64 s[6:7], vcc, s[6:7]
	s_and_saveexec_b64 s[28:29], s[6:7]
	s_cbranch_execz .Luc_skip2
	s_mov_b64 s[78:79], 0
	s_cmp_eq_u32 s100, 0
	s_cbranch_scc1 .Luc_fast2
	v_add_u32_e32 v52, 2, v45
	v_mov_b32_e32 v53, 0xff
	v_cmp_gt_i32_e32 vcc, s49, v52
	v_mov_b32_e32 v46, 0xfff
	s_nop 0
	v_cndmask_b32_e32 v53, v53, v46, vcc
	v_and_b32_e32 v52, v52, v53
	v_cmp_ne_u32_e32 vcc, 0, v52
	v_cmp_ne_u32_e64 s[6:7], v52, v53
	s_mov_b64 s[78:79], 0
	s_and_b64 s[76:77], vcc, s[6:7]
	s_xor_b64 s[76:77], s[76:77], exec
	s_cbranch_scc0 .Luc_fast2
	v_cndmask_b32_e32 v98, 0, v98, vcc
	v_cndmask_b32_e32 v99, 0, v99, vcc
	v_cndmask_b32_e32 v100, 0, v100, vcc
	v_cndmask_b32_e32 v101, 0, v101, vcc
	v_cndmask_b32_e32 v102, 0, v102, vcc
	v_cndmask_b32_e32 v103, 0, v103, vcc
	v_cndmask_b32_e32 v104, 0, v104, vcc
	v_cndmask_b32_e32 v105, 0, v105, vcc
	v_cndmask_b32_e32 v106, 0, v106, vcc
	v_cndmask_b32_e32 v107, 0, v107, vcc
	v_cndmask_b32_e32 v108, 0, v108, vcc
	v_cndmask_b32_e32 v109, 0, v109, vcc
	v_cndmask_b32_e32 v110, 0, v110, vcc
	v_cndmask_b32_e32 v111, 0, v111, vcc
	v_cndmask_b32_e32 v112, 0, v112, vcc
	v_cndmask_b32_e32 v113, 0, v113, vcc
	v_mov_b64_e32 v[2:3], v[82:83]
	v_mov_b64_e32 v[4:5], v[84:85]
	v_mov_b64_e32 v[6:7], v[86:87]
	v_mov_b64_e32 v[8:9], v[88:89]
	v_mov_b64_e32 v[10:11], v[90:91]
	v_mov_b64_e32 v[12:13], v[92:93]
	v_mov_b64_e32 v[14:15], v[94:95]
	v_mov_b64_e32 v[16:17], v[96:97]
	v_cndmask_b32_e64 v82, 0, v82, s[6:7]
	v_cndmask_b32_e64 v83, 0, v83, s[6:7]
	v_cndmask_b32_e64 v84, 0, v84, s[6:7]
	v_cndmask_b32_e64 v85, 0, v85, s[6:7]
	v_cndmask_b32_e64 v86, 0, v86, s[6:7]
	v_cndmask_b32_e64 v87, 0, v87, s[6:7]
	v_cndmask_b32_e64 v88, 0, v88, s[6:7]
	v_cndmask_b32_e64 v89, 0, v89, s[6:7]
	v_cndmask_b32_e64 v90, 0, v90, s[6:7]
	v_cndmask_b32_e64 v91, 0, v91, s[6:7]
	v_cndmask_b32_e64 v92, 0, v92, s[6:7]
	v_cndmask_b32_e64 v93, 0, v93, s[6:7]
	v_cndmask_b32_e64 v94, 0, v94, s[6:7]
	v_cndmask_b32_e64 v95, 0, v95, s[6:7]
	v_cndmask_b32_e64 v96, 0, v96, s[6:7]
	v_cndmask_b32_e64 v97, 0, v97, s[6:7]
	s_mov_b64 s[78:79], -1

.Luc_skip2:
	s_or_b64 exec, exec, s[28:29]
	v_readlane_b32 s28, v255, 19
	v_lshl_add_u64 v[50:51], v[50:51], 0, s[38:39]
	s_waitcnt lgkmcnt(0)
	v_lshlrev_b32_e32 v98, 16, v122
	v_and_b32_e32 v99, 0xffff0000, v122
	v_lshlrev_b32_e32 v100, 16, v123
	v_and_b32_e32 v101, 0xffff0000, v123
	v_lshlrev_b32_e32 v102, 16, v124
	v_and_b32_e32 v103, 0xffff0000, v124
	v_lshlrev_b32_e32 v104, 16, v125
	v_and_b32_e32 v105, 0xffff0000, v125
	v_lshlrev_b32_e32 v106, 16, v126
	v_and_b32_e32 v107, 0xffff0000, v126
	v_lshlrev_b32_e32 v108, 16, v127
	v_and_b32_e32 v109, 0xffff0000, v127
	v_lshlrev_b32_e32 v110, 16, v128
	v_and_b32_e32 v111, 0xffff0000, v128
	v_lshlrev_b32_e32 v112, 16, v129
	v_and_b32_e32 v113, 0xffff0000, v129
	ds_read_b128 v[114:117], v54 offset:3264
	ds_read_b128 v[118:121], v54 offset:3520
	s_movk_i32 s6, 252
	v_cmp_gt_i32_e32 vcc, s6, v49
	s_sub_i32 s6, s28, 3
	v_cmp_gt_i32_e64 s[6:7], s6, v45
	s_and_b64 s[6:7], vcc, s[6:7]
	s_and_saveexec_b64 s[28:29], s[6:7]
	s_cbranch_execz .Luc_skip3
	s_mov_b64 s[78:79], 0
	s_cmp_eq_u32 s100, 0
	s_cbranch_scc1 .Luc_fast3
	v_add_u32_e32 v52, 3, v45
	v_mov_b32_e32 v53, 0xff
	v_cmp_gt_i32_e32 vcc, s49, v52
	v_mov_b32_e32 v46, 0xfff
	s_nop 0
	v_cndmask_b32_e32 v53, v53, v46, vcc
	v_and_b32_e32 v52, v52, v53
	v_cmp_ne_u32_e32 vcc, 0, v52
	v_cmp_ne_u32_e64 s[6:7], v52, v53
	s_mov_b64 s[78:79], 0
	s_and_b64 s[76:77], vcc, s[6:7]
	s_xor_b64 s[76:77], s[76:77], exec
	s_cbranch_scc0 .Luc_fast3
	v_cndmask_b32_e32 v66, 0, v66, vcc
	v_cndmask_b32_e32 v67, 0, v67, vcc
	v_cndmask_b32_e32 v68, 0, v68, vcc
	v_cndmask_b32_e32 v69, 0, v69, vcc
	v_cndmask_b32_e32 v70, 0, v70, vcc
	v_cndmask_b32_e32 v71, 0, v71, vcc
	v_cndmask_b32_e32 v72, 0, v72, vcc
	v_cndmask_b32_e32 v73, 0, v73, vcc
	v_cndmask_b32_e32 v74, 0, v74, vcc
	v_cndmask_b32_e32 v75, 0, v75, vcc
	v_cndmask_b32_e32 v76, 0, v76, vcc
	v_cndmask_b32_e32 v77, 0, v77, vcc
	v_cndmask_b32_e32 v78, 0, v78, vcc
	v_cndmask_b32_e32 v79, 0, v79, vcc
	v_cndmask_b32_e32 v80, 0, v80, vcc
	v_cndmask_b32_e32 v81, 0, v81, vcc
	v_mov_b64_e32 v[2:3], v[98:99]
	v_mov_b64_e32 v[4:5], v[100:101]
	v_mov_b64_e32 v[6:7], v[102:103]
	v_mov_b64_e32 v[8:9], v[104:105]
	v_mov_b64_e32 v[10:11], v[106:107]
	v_mov_b64_e32 v[12:13], v[108:109]
	v_mov_b64_e32 v[14:15], v[110:111]
	v_mov_b64_e32 v[16:17], v[112:113]
	v_cndmask_b32_e64 v98, 0, v98, s[6:7]
	v_cndmask_b32_e64 v99, 0, v99, s[6:7]
	v_cndmask_b32_e64 v100, 0, v100, s[6:7]
	v_cndmask_b32_e64 v101, 0, v101, s[6:7]
	v_cndmask_b32_e64 v102, 0, v102, s[6:7]
	v_cndmask_b32_e64 v103, 0, v103, s[6:7]
	v_cndmask_b32_e64 v104, 0, v104, s[6:7]
	v_cndmask_b32_e64 v105, 0, v105, s[6:7]
	v_cndmask_b32_e64 v106, 0, v106, s[6:7]
	v_cndmask_b32_e64 v107, 0, v107, s[6:7]
	v_cndmask_b32_e64 v108, 0, v108, s[6:7]
	v_cndmask_b32_e64 v109, 0, v109, s[6:7]
	v_cndmask_b32_e64 v110, 0, v110, s[6:7]
	v_cndmask_b32_e64 v111, 0, v111, s[6:7]
	v_cndmask_b32_e64 v112, 0, v112, s[6:7]
	v_cndmask_b32_e64 v113, 0, v113, s[6:7]
	s_mov_b64 s[78:79], -1

.Luc_skip3:
	s_or_b64 exec, exec, s[28:29]
	v_readlane_b32 s28, v255, 19
	v_lshl_add_u64 v[50:51], v[50:51], 0, s[38:39]
	s_waitcnt lgkmcnt(0)
	v_lshlrev_b32_e32 v66, 16, v114
	v_and_b32_e32 v67, 0xffff0000, v114
	v_lshlrev_b32_e32 v68, 16, v115
	v_and_b32_e32 v69, 0xffff0000, v115
	v_lshlrev_b32_e32 v70, 16, v116
	v_and_b32_e32 v71, 0xffff0000, v116
	v_lshlrev_b32_e32 v72, 16, v117
	v_and_b32_e32 v73, 0xffff0000, v117
	v_lshlrev_b32_e32 v74, 16, v118
	v_and_b32_e32 v75, 0xffff0000, v118
	v_lshlrev_b32_e32 v76, 16, v119
	v_and_b32_e32 v77, 0xffff0000, v119
	v_lshlrev_b32_e32 v78, 16, v120
	v_and_b32_e32 v79, 0xffff0000, v120
	v_lshlrev_b32_e32 v80, 16, v121
	v_and_b32_e32 v81, 0xffff0000, v121
	ds_read_b128 v[122:125], v54 offset:3808
	ds_read_b128 v[126:129], v54 offset:4064
	s_movk_i32 s6, 251
	v_cmp_gt_i32_e32 vcc, s6, v49
	s_sub_i32 s6, s28, 4
	v_cmp_gt_i32_e64 s[6:7], s6, v45
	s_and_b64 s[6:7], vcc, s[6:7]
	s_and_saveexec_b64 s[28:29], s[6:7]
	s_cbranch_execz .Luc_skip4
	s_mov_b64 s[78:79], 0
	s_cmp_eq_u32 s100, 0
	s_cbranch_scc1 .Luc_fast4
	v_add_u32_e32 v52, 4, v45
	v_mov_b32_e32 v53, 0xff
	v_cmp_gt_i32_e32 vcc, s49, v52
	v_mov_b32_e32 v46, 0xfff
	s_nop 0
	v_cndmask_b32_e32 v53, v53, v46, vcc
	v_and_b32_e32 v52, v52, v53
	v_cmp_ne_u32_e32 vcc, 0, v52
	v_cmp_ne_u32_e64 s[6:7], v52, v53
	s_mov_b64 s[78:79], 0
	s_and_b64 s[76:77], vcc, s[6:7]
	s_xor_b64 s[76:77], s[76:77], exec
	s_cbranch_scc0 .Luc_fast4
	v_cndmask_b32_e32 v82, 0, v82, vcc
	v_cndmask_b32_e32 v83, 0, v83, vcc
	v_cndmask_b32_e32 v84, 0, v84, vcc
	v_cndmask_b32_e32 v85, 0, v85, vcc
	v_cndmask_b32_e32 v86, 0, v86, vcc
	v_cndmask_b32_e32 v87, 0, v87, vcc
	v_cndmask_b32_e32 v88, 0, v88, vcc
	v_cndmask_b32_e32 v89, 0, v89, vcc
	v_cndmask_b32_e32 v90, 0, v90, vcc
	v_cndmask_b32_e32 v91, 0, v91, vcc
	v_cndmask_b32_e32 v92, 0, v92, vcc
	v_cndmask_b32_e32 v93, 0, v93, vcc
	v_cndmask_b32_e32 v94, 0, v94, vcc
	v_cndmask_b32_e32 v95, 0, v95, vcc
	v_cndmask_b32_e32 v96, 0, v96, vcc
	v_cndmask_b32_e32 v97, 0, v97, vcc
	v_mov_b64_e32 v[2:3], v[66:67]
	v_mov_b64_e32 v[4:5], v[68:69]
	v_mov_b64_e32 v[6:7], v[70:71]
	v_mov_b64_e32 v[8:9], v[72:73]
	v_mov_b64_e32 v[10:11], v[74:75]
	v_mov_b64_e32 v[12:13], v[76:77]
	v_mov_b64_e32 v[14:15], v[78:79]
	v_mov_b64_e32 v[16:17], v[80:81]
	v_cndmask_b32_e64 v66, 0, v66, s[6:7]
	v_cndmask_b32_e64 v67, 0, v67, s[6:7]
	v_cndmask_b32_e64 v68, 0, v68, s[6:7]
	v_cndmask_b32_e64 v69, 0, v69, s[6:7]
	v_cndmask_b32_e64 v70, 0, v70, s[6:7]
	v_cndmask_b32_e64 v71, 0, v71, s[6:7]
	v_cndmask_b32_e64 v72, 0, v72, s[6:7]
	v_cndmask_b32_e64 v73, 0, v73, s[6:7]
	v_cndmask_b32_e64 v74, 0, v74, s[6:7]
	v_cndmask_b32_e64 v75, 0, v75, s[6:7]
	v_cndmask_b32_e64 v76, 0, v76, s[6:7]
	v_cndmask_b32_e64 v77, 0, v77, s[6:7]
	v_cndmask_b32_e64 v78, 0, v78, s[6:7]
	v_cndmask_b32_e64 v79, 0, v79, s[6:7]
	v_cndmask_b32_e64 v80, 0, v80, s[6:7]
	v_cndmask_b32_e64 v81, 0, v81, s[6:7]
	s_mov_b64 s[78:79], -1

.Luc_skip4:
	s_or_b64 exec, exec, s[28:29]
	v_readlane_b32 s28, v255, 19
	v_lshl_add_u64 v[50:51], v[50:51], 0, s[38:39]
	s_waitcnt lgkmcnt(0)
	v_lshlrev_b32_e32 v82, 16, v122
	v_and_b32_e32 v83, 0xffff0000, v122
	v_lshlrev_b32_e32 v84, 16, v123
	v_and_b32_e32 v85, 0xffff0000, v123
	v_lshlrev_b32_e32 v86, 16, v124
	v_and_b32_e32 v87, 0xffff0000, v124
	v_lshlrev_b32_e32 v88, 16, v125
	v_and_b32_e32 v89, 0xffff0000, v125
	v_lshlrev_b32_e32 v90, 16, v126
	v_and_b32_e32 v91, 0xffff0000, v126
	v_lshlrev_b32_e32 v92, 16, v127
	v_and_b32_e32 v93, 0xffff0000, v127
	v_lshlrev_b32_e32 v94, 16, v128
	v_and_b32_e32 v95, 0xffff0000, v128
	v_lshlrev_b32_e32 v96, 16, v129
	v_and_b32_e32 v97, 0xffff0000, v129
	ds_read_b128 v[114:117], v54 offset:4352
	ds_read_b128 v[118:121], v54 offset:4608
	s_movk_i32 s6, 250
	v_cmp_gt_i32_e32 vcc, s6, v49
	s_sub_i32 s6, s28, 5
	v_cmp_gt_i32_e64 s[6:7], s6, v45
	s_and_b64 s[6:7], vcc, s[6:7]
	s_and_saveexec_b64 s[28:29], s[6:7]
	s_cbranch_execz .Luc_skip5
	s_mov_b64 s[78:79], 0
	s_cmp_eq_u32 s100, 0
	s_cbranch_scc1 .Luc_fast5
	v_add_u32_e32 v52, 5, v45
	v_mov_b32_e32 v53, 0xff
	v_cmp_gt_i32_e32 vcc, s49, v52
	v_mov_b32_e32 v46, 0xfff
	s_nop 0
	v_cndmask_b32_e32 v53, v53, v46, vcc
	v_and_b32_e32 v52, v52, v53
	v_cmp_ne_u32_e32 vcc, 0, v52
	v_cmp_ne_u32_e64 s[6:7], v52, v53
	s_mov_b64 s[78:79], 0
	s_and_b64 s[76:77], vcc, s[6:7]
	s_xor_b64 s[76:77], s[76:77], exec
	s_cbranch_scc0 .Luc_fast5
	v_cndmask_b32_e32 v98, 0, v98, vcc
	v_cndmask_b32_e32 v99, 0, v99, vcc
	v_cndmask_b32_e32 v100, 0, v100, vcc
	v_cndmask_b32_e32 v101, 0, v101, vcc
	v_cndmask_b32_e32 v102, 0, v102, vcc
	v_cndmask_b32_e32 v103, 0, v103, vcc
	v_cndmask_b32_e32 v104, 0, v104, vcc
	v_cndmask_b32_e32 v105, 0, v105, vcc
	v_cndmask_b32_e32 v106, 0, v106, vcc
	v_cndmask_b32_e32 v107, 0, v107, vcc
	v_cndmask_b32_e32 v108, 0, v108, vcc
	v_cndmask_b32_e32 v109, 0, v109, vcc
	v_cndmask_b32_e32 v110, 0, v110, vcc
	v_cndmask_b32_e32 v111, 0, v111, vcc
	v_cndmask_b32_e32 v112, 0, v112, vcc
	v_cndmask_b32_e32 v113, 0, v113, vcc
	v_mov_b64_e32 v[2:3], v[82:83]
	v_mov_b64_e32 v[4:5], v[84:85]
	v_mov_b64_e32 v[6:7], v[86:87]
	v_mov_b64_e32 v[8:9], v[88:89]
	v_mov_b64_e32 v[10:11], v[90:91]
	v_mov_b64_e32 v[12:13], v[92:93]
	v_mov_b64_e32 v[14:15], v[94:95]
	v_mov_b64_e32 v[16:17], v[96:97]
	v_cndmask_b32_e64 v82, 0, v82, s[6:7]
	v_cndmask_b32_e64 v83, 0, v83, s[6:7]
	v_cndmask_b32_e64 v84, 0, v84, s[6:7]
	v_cndmask_b32_e64 v85, 0, v85, s[6:7]
	v_cndmask_b32_e64 v86, 0, v86, s[6:7]
	v_cndmask_b32_e64 v87, 0, v87, s[6:7]
	v_cndmask_b32_e64 v88, 0, v88, s[6:7]
	v_cndmask_b32_e64 v89, 0, v89, s[6:7]
	v_cndmask_b32_e64 v90, 0, v90, s[6:7]
	v_cndmask_b32_e64 v91, 0, v91, s[6:7]
	v_cndmask_b32_e64 v92, 0, v92, s[6:7]
	v_cndmask_b32_e64 v93, 0, v93, s[6:7]
	v_cndmask_b32_e64 v94, 0, v94, s[6:7]
	v_cndmask_b32_e64 v95, 0, v95, s[6:7]
	v_cndmask_b32_e64 v96, 0, v96, s[6:7]
	v_cndmask_b32_e64 v97, 0, v97, s[6:7]
	s_mov_b64 s[78:79], -1

.Luc_skip5:
	s_or_b64 exec, exec, s[28:29]
	v_readlane_b32 s28, v255, 19
	v_lshl_add_u64 v[50:51], v[50:51], 0, s[38:39]
	s_waitcnt lgkmcnt(0)
	v_lshlrev_b32_e32 v98, 16, v114
	v_and_b32_e32 v99, 0xffff0000, v114
	v_lshlrev_b32_e32 v100, 16, v115
	v_and_b32_e32 v101, 0xffff0000, v115
	v_lshlrev_b32_e32 v102, 16, v116
	v_and_b32_e32 v103, 0xffff0000, v116
	v_lshlrev_b32_e32 v104, 16, v117
	v_and_b32_e32 v105, 0xffff0000, v117
	v_lshlrev_b32_e32 v106, 16, v118
	v_and_b32_e32 v107, 0xffff0000, v118
	v_lshlrev_b32_e32 v108, 16, v119
	v_and_b32_e32 v109, 0xffff0000, v119
	v_lshlrev_b32_e32 v110, 16, v120
	v_and_b32_e32 v111, 0xffff0000, v120
	v_lshlrev_b32_e32 v112, 16, v121
	v_and_b32_e32 v113, 0xffff0000, v121
	ds_read_b128 v[122:125], v54 offset:4896
	ds_read_b128 v[126:129], v54 offset:5152
	s_movk_i32 s6, 249
	v_cmp_gt_i32_e32 vcc, s6, v49
	s_sub_i32 s6, s28, 6
	v_cmp_gt_i32_e64 s[6:7], s6, v45
	s_and_b64 s[6:7], vcc, s[6:7]
	s_and_saveexec_b64 s[28:29], s[6:7]
	s_cbranch_execz .Luc_skip6
	s_mov_b64 s[78:79], 0
	s_cmp_eq_u32 s100, 0
	s_cbranch_scc1 .Luc_fast6
	v_add_u32_e32 v52, 6, v45
	v_mov_b32_e32 v53, 0xff
	v_cmp_gt_i32_e32 vcc, s49, v52
	v_mov_b32_e32 v46, 0xfff
	s_nop 0
	v_cndmask_b32_e32 v53, v53, v46, vcc
	v_and_b32_e32 v52, v52, v53
	v_cmp_ne_u32_e32 vcc, 0, v52
	v_cmp_ne_u32_e64 s[6:7], v52, v53
	s_mov_b64 s[78:79], 0
	s_and_b64 s[76:77], vcc, s[6:7]
	s_xor_b64 s[76:77], s[76:77], exec
	s_cbranch_scc0 .Luc_fast6
	v_cndmask_b32_e32 v66, 0, v66, vcc
	v_cndmask_b32_e32 v67, 0, v67, vcc
	v_cndmask_b32_e32 v68, 0, v68, vcc
	v_cndmask_b32_e32 v69, 0, v69, vcc
	v_cndmask_b32_e32 v70, 0, v70, vcc
	v_cndmask_b32_e32 v71, 0, v71, vcc
	v_cndmask_b32_e32 v72, 0, v72, vcc
	v_cndmask_b32_e32 v73, 0, v73, vcc
	v_cndmask_b32_e32 v74, 0, v74, vcc
	v_cndmask_b32_e32 v75, 0, v75, vcc
	v_cndmask_b32_e32 v76, 0, v76, vcc
	v_cndmask_b32_e32 v77, 0, v77, vcc
	v_cndmask_b32_e32 v78, 0, v78, vcc
	v_cndmask_b32_e32 v79, 0, v79, vcc
	v_cndmask_b32_e32 v80, 0, v80, vcc
	v_cndmask_b32_e32 v81, 0, v81, vcc
	v_mov_b64_e32 v[2:3], v[98:99]
	v_mov_b64_e32 v[4:5], v[100:101]
	v_mov_b64_e32 v[6:7], v[102:103]
	v_mov_b64_e32 v[8:9], v[104:105]
	v_mov_b64_e32 v[10:11], v[106:107]
	v_mov_b64_e32 v[12:13], v[108:109]
	v_mov_b64_e32 v[14:15], v[110:111]
	v_mov_b64_e32 v[16:17], v[112:113]
	v_cndmask_b32_e64 v98, 0, v98, s[6:7]
	v_cndmask_b32_e64 v99, 0, v99, s[6:7]
	v_cndmask_b32_e64 v100, 0, v100, s[6:7]
	v_cndmask_b32_e64 v101, 0, v101, s[6:7]
	v_cndmask_b32_e64 v102, 0, v102, s[6:7]
	v_cndmask_b32_e64 v103, 0, v103, s[6:7]
	v_cndmask_b32_e64 v104, 0, v104, s[6:7]
	v_cndmask_b32_e64 v105, 0, v105, s[6:7]
	v_cndmask_b32_e64 v106, 0, v106, s[6:7]
	v_cndmask_b32_e64 v107, 0, v107, s[6:7]
	v_cndmask_b32_e64 v108, 0, v108, s[6:7]
	v_cndmask_b32_e64 v109, 0, v109, s[6:7]
	v_cndmask_b32_e64 v110, 0, v110, s[6:7]
	v_cndmask_b32_e64 v111, 0, v111, s[6:7]
	v_cndmask_b32_e64 v112, 0, v112, s[6:7]
	v_cndmask_b32_e64 v113, 0, v113, s[6:7]
	s_mov_b64 s[78:79], -1

.Luc_skip6:
	s_or_b64 exec, exec, s[28:29]
	v_readlane_b32 s28, v255, 19
	v_lshl_add_u64 v[50:51], v[50:51], 0, s[38:39]
	s_waitcnt lgkmcnt(0)
	v_lshlrev_b32_e32 v66, 16, v122
	v_and_b32_e32 v67, 0xffff0000, v122
	v_lshlrev_b32_e32 v68, 16, v123
	v_and_b32_e32 v69, 0xffff0000, v123
	v_lshlrev_b32_e32 v70, 16, v124
	v_and_b32_e32 v71, 0xffff0000, v124
	v_lshlrev_b32_e32 v72, 16, v125
	v_and_b32_e32 v73, 0xffff0000, v125
	v_lshlrev_b32_e32 v74, 16, v126
	v_and_b32_e32 v75, 0xffff0000, v126
	v_lshlrev_b32_e32 v76, 16, v127
	v_and_b32_e32 v77, 0xffff0000, v127
	v_lshlrev_b32_e32 v78, 16, v128
	v_and_b32_e32 v79, 0xffff0000, v128
	v_lshlrev_b32_e32 v80, 16, v129
	v_and_b32_e32 v81, 0xffff0000, v129
	s_movk_i32 s6, 248
	v_cmp_gt_i32_e32 vcc, s6, v49
	s_sub_i32 s6, s28, 7
	v_cmp_gt_i32_e64 s[6:7], s6, v45
	s_and_b64 s[6:7], vcc, s[6:7]
	s_and_saveexec_b64 s[28:29], s[6:7]
	s_cbranch_execz .Luc_skip7
	s_mov_b64 s[78:79], 0
	s_cmp_eq_u32 s100, 0
	s_cbranch_scc1 .Luc_fast7
	v_add_u32_e32 v52, 7, v45
	v_mov_b32_e32 v53, 0xff
	v_cmp_gt_i32_e32 vcc, s49, v52
	v_mov_b32_e32 v46, 0xfff
	s_nop 0
	v_cndmask_b32_e32 v53, v53, v46, vcc
	v_and_b32_e32 v52, v52, v53
	v_cmp_ne_u32_e32 vcc, 0, v52
	v_cmp_ne_u32_e64 s[6:7], v52, v53
	s_mov_b64 s[78:79], 0
	s_and_b64 s[76:77], vcc, s[6:7]
	s_xor_b64 s[76:77], s[76:77], exec
	s_cbranch_scc0 .Luc_fast7
	v_cndmask_b32_e32 v82, 0, v82, vcc
	v_cndmask_b32_e32 v83, 0, v83, vcc
	v_cndmask_b32_e32 v84, 0, v84, vcc
	v_cndmask_b32_e32 v85, 0, v85, vcc
	v_cndmask_b32_e32 v86, 0, v86, vcc
	v_cndmask_b32_e32 v87, 0, v87, vcc
	v_cndmask_b32_e32 v88, 0, v88, vcc
	v_cndmask_b32_e32 v89, 0, v89, vcc
	v_cndmask_b32_e32 v90, 0, v90, vcc
	v_cndmask_b32_e32 v91, 0, v91, vcc
	v_cndmask_b32_e32 v92, 0, v92, vcc
	v_cndmask_b32_e32 v93, 0, v93, vcc
	v_cndmask_b32_e32 v94, 0, v94, vcc
	v_cndmask_b32_e32 v95, 0, v95, vcc
	v_cndmask_b32_e32 v96, 0, v96, vcc
	v_cndmask_b32_e32 v97, 0, v97, vcc
	v_mov_b64_e32 v[2:3], v[66:67]
	v_mov_b64_e32 v[4:5], v[68:69]
	v_mov_b64_e32 v[6:7], v[70:71]
	v_mov_b64_e32 v[8:9], v[72:73]
	v_mov_b64_e32 v[10:11], v[74:75]
	v_mov_b64_e32 v[12:13], v[76:77]
	v_mov_b64_e32 v[14:15], v[78:79]
	v_mov_b64_e32 v[16:17], v[80:81]
	v_cndmask_b32_e64 v66, 0, v66, s[6:7]
	v_cndmask_b32_e64 v67, 0, v67, s[6:7]
	v_cndmask_b32_e64 v68, 0, v68, s[6:7]
	v_cndmask_b32_e64 v69, 0, v69, s[6:7]
	v_cndmask_b32_e64 v70, 0, v70, s[6:7]
	v_cndmask_b32_e64 v71, 0, v71, s[6:7]
	v_cndmask_b32_e64 v72, 0, v72, s[6:7]
	v_cndmask_b32_e64 v73, 0, v73, s[6:7]
	v_cndmask_b32_e64 v74, 0, v74, s[6:7]
	v_cndmask_b32_e64 v75, 0, v75, s[6:7]
	v_cndmask_b32_e64 v76, 0, v76, s[6:7]
	v_cndmask_b32_e64 v77, 0, v77, s[6:7]
	v_cndmask_b32_e64 v78, 0, v78, s[6:7]
	v_cndmask_b32_e64 v79, 0, v79, s[6:7]
	v_cndmask_b32_e64 v80, 0, v80, s[6:7]
	v_cndmask_b32_e64 v81, 0, v81, s[6:7]
	s_mov_b64 s[78:79], -1
